# stack: epilogue rs hoist + retention cvt pipelining + tr_matrix gain-load de-serialisation
# baseline (speedup 1.0000x reference)
.LBB0_13:
	s_mul_hi_i32 s16, s23, 0x2aaaaaab
	s_lshr_b32 s17, s16, 31
	s_ashr_i32 s16, s16, 5
	s_add_i32 s17, s16, s17
	s_mul_i32 s16, s17, 0xffffff40
	s_add_i32 s19, s23, s16
	s_lshl_b32 s16, s17, 6
	s_mulk_i32 s17, 0xd000
	s_add_i32 s18, s0, s17
	s_andn2_b32 s19, s19, 31
	s_cmp_eq_u32 s19, 32
	s_cselect_b64 vcc, -1, 0
	s_ashr_i32 s19, s18, 31
	v_or_b32_e32 v51, s16, v39
	v_lshl_add_u64 v[46:47], s[18:19], 2, v[42:43]
	v_mad_i64_i32 v[2:3], s[24:25], v51, s22, v[46:47]
	global_load_dwordx4 v[2:5], v[2:3], off
	v_cndmask_b32_e32 v44, 1.0, v45, vcc
	s_and_b64 vcc, exec, s[4:5]
	v_mov_b32_e32 v48, v44
	s_cbranch_vccnz .LBB0_15
	v_and_b32_e32 v6, 0x7c3, v51
	v_lshlrev_b32_e32 v6, 2, v6
	global_load_dword v150, v6, s[14:15]
	global_load_dword v151, v6, s[14:15] offset:16
	global_load_dword v152, v6, s[14:15] offset:32
	global_load_dword v153, v6, s[14:15] offset:48
	global_load_dword v154, v6, s[14:15] offset:64
	global_load_dword v155, v6, s[14:15] offset:80
	global_load_dword v156, v6, s[14:15] offset:96
	global_load_dword v157, v6, s[14:15] offset:112
	global_load_dword v158, v6, s[14:15] offset:128
	global_load_dword v159, v6, s[14:15] offset:144
	global_load_dword v160, v6, s[14:15] offset:160
	global_load_dword v161, v6, s[14:15] offset:176
	global_load_dword v162, v6, s[14:15] offset:192
	global_load_dword v163, v6, s[14:15] offset:208
	global_load_dword v164, v6, s[14:15] offset:224
	global_load_dword v165, v6, s[14:15] offset:240
	s_waitcnt vmcnt(0)
	v_mul_f32_e32 v48, v44, v150
.LBB0_15:
	v_or_b32_e32 v10, 4, v51
	v_mad_i64_i32 v[6:7], s[24:25], v10, s22, v[46:47]
	global_load_dwordx4 v[6:9], v[6:7], off
	s_and_b64 vcc, exec, s[4:5]
	v_mov_b32_e32 v50, v44
	s_cbranch_vccnz .LBB0_17
	s_nop 0
	v_mul_f32_e32 v50, v44, v151
.LBB0_17:
	v_or_b32_e32 v14, 8, v51
	v_mad_i64_i32 v[10:11], s[24:25], v14, s22, v[46:47]
	global_load_dwordx4 v[10:13], v[10:11], off
	s_and_b64 vcc, exec, s[4:5]
	v_mov_b32_e32 v52, v44
	s_cbranch_vccnz .LBB0_19
	s_nop 0
	v_mul_f32_e32 v52, v44, v152
.LBB0_19:
	v_or_b32_e32 v18, 12, v51
	v_mad_i64_i32 v[14:15], s[24:25], v18, s22, v[46:47]
	global_load_dwordx4 v[14:17], v[14:15], off
	s_and_b64 vcc, exec, s[4:5]
	v_mov_b32_e32 v54, v44
	s_cbranch_vccnz .LBB0_21
	s_nop 0
	v_mul_f32_e32 v54, v44, v153
.LBB0_21:
	v_or_b32_e32 v22, 16, v51
	v_mad_i64_i32 v[18:19], s[24:25], v22, s22, v[46:47]
	global_load_dwordx4 v[18:21], v[18:19], off
	s_and_b64 vcc, exec, s[4:5]
	v_mov_b32_e32 v56, v44
	s_cbranch_vccnz .LBB0_23
	s_nop 0
	v_mul_f32_e32 v56, v44, v154
.LBB0_23:
	v_or_b32_e32 v22, 20, v51
	v_mad_i64_i32 v[24:25], s[24:25], v22, s22, v[46:47]
	global_load_dwordx4 v[26:29], v[24:25], off
	s_and_b64 vcc, exec, s[4:5]
	v_mov_b32_e32 v58, v44
	s_cbranch_vccnz .LBB0_25
	s_nop 0
	v_mul_f32_e32 v58, v44, v155
.LBB0_25:
	v_or_b32_e32 v22, 24, v51
	v_mad_i64_i32 v[24:25], s[24:25], v22, s22, v[46:47]
	global_load_dwordx4 v[30:33], v[24:25], off
	s_and_b64 vcc, exec, s[4:5]
	v_mov_b32_e32 v60, v44
	s_cbranch_vccnz .LBB0_27
	s_nop 0
	v_mul_f32_e32 v60, v44, v156
.LBB0_27:
	v_or_b32_e32 v22, 28, v51
	v_mad_i64_i32 v[24:25], s[24:25], v22, s22, v[46:47]
	global_load_dwordx4 v[34:37], v[24:25], off
	s_and_b64 vcc, exec, s[4:5]
	v_mov_b32_e32 v62, v44
	s_cbranch_vccnz .LBB0_29
	s_nop 0
	v_mul_f32_e32 v62, v44, v157
.LBB0_29:
	v_or_b32_e32 v53, 32, v51
	v_mad_i64_i32 v[22:23], s[24:25], v53, s22, v[46:47]
	global_load_dwordx4 v[22:25], v[22:23], off
	s_waitcnt vmcnt(8)
	v_pk_mul_f32 v[4:5], v[4:5], v[48:49] op_sel_hi:[1,0]
	v_pk_mul_f32 v[2:3], v[2:3], v[48:49] op_sel_hi:[1,0]
	ds_write_b128 v49, v[2:5]
	s_waitcnt vmcnt(7)
	v_pk_mul_f32 v[4:5], v[8:9], v[50:51] op_sel_hi:[1,0]
	v_pk_mul_f32 v[2:3], v[6:7], v[50:51] op_sel_hi:[1,0]
	ds_write_b128 v49, v[2:5] offset:1088
	s_waitcnt vmcnt(6)
	v_pk_mul_f32 v[4:5], v[12:13], v[52:53] op_sel_hi:[1,0]
	v_pk_mul_f32 v[2:3], v[10:11], v[52:53] op_sel_hi:[1,0]
	ds_write_b128 v49, v[2:5] offset:2176
	s_waitcnt vmcnt(5)
	v_pk_mul_f32 v[4:5], v[16:17], v[54:55] op_sel_hi:[1,0]
	v_pk_mul_f32 v[2:3], v[14:15], v[54:55] op_sel_hi:[1,0]
	ds_write_b128 v49, v[2:5] offset:3264
	s_waitcnt vmcnt(4)
	v_pk_mul_f32 v[4:5], v[20:21], v[56:57] op_sel_hi:[1,0]
	v_pk_mul_f32 v[2:3], v[18:19], v[56:57] op_sel_hi:[1,0]
	ds_write_b128 v49, v[2:5] offset:4352
	s_waitcnt vmcnt(3)
	v_pk_mul_f32 v[4:5], v[28:29], v[58:59] op_sel_hi:[1,0]
	v_pk_mul_f32 v[2:3], v[26:27], v[58:59] op_sel_hi:[1,0]
	ds_write_b128 v49, v[2:5] offset:5440
	s_waitcnt vmcnt(2)
	v_pk_mul_f32 v[4:5], v[32:33], v[60:61] op_sel_hi:[1,0]
	v_pk_mul_f32 v[2:3], v[30:31], v[60:61] op_sel_hi:[1,0]
	ds_write_b128 v49, v[2:5] offset:6528
	s_waitcnt vmcnt(1)
	v_pk_mul_f32 v[4:5], v[36:37], v[62:63] op_sel_hi:[1,0]
	v_pk_mul_f32 v[2:3], v[34:35], v[62:63] op_sel_hi:[1,0]
	s_and_b64 vcc, exec, s[4:5]
	v_mov_b32_e32 v34, v44
	ds_write_b128 v49, v[2:5] offset:7616
	s_cbranch_vccnz .LBB0_31
	s_nop 0
	v_mul_f32_e32 v34, v44, v158
.LBB0_31:
	v_or_b32_e32 v6, 36, v51
	v_mad_i64_i32 v[2:3], s[24:25], v6, s22, v[46:47]
	global_load_dwordx4 v[2:5], v[2:3], off
	s_and_b64 vcc, exec, s[4:5]
	v_mov_b32_e32 v36, v44
	s_cbranch_vccnz .LBB0_33
	s_nop 0
	v_mul_f32_e32 v36, v44, v159
.LBB0_33:
	v_or_b32_e32 v10, 40, v51
	v_mad_i64_i32 v[6:7], s[24:25], v10, s22, v[46:47]
	global_load_dwordx4 v[6:9], v[6:7], off
	s_and_b64 vcc, exec, s[4:5]
	v_mov_b32_e32 v48, v44
	s_cbranch_vccnz .LBB0_35
	s_nop 0
	v_mul_f32_e32 v48, v44, v160
.LBB0_35:
	v_or_b32_e32 v14, 44, v51
	v_mad_i64_i32 v[10:11], s[24:25], v14, s22, v[46:47]
	global_load_dwordx4 v[10:13], v[10:11], off
	s_and_b64 vcc, exec, s[4:5]
	v_mov_b32_e32 v50, v44
	s_cbranch_vccnz .LBB0_37
	s_nop 0
	v_mul_f32_e32 v50, v44, v161
.LBB0_37:
	v_or_b32_e32 v18, 48, v51
	v_mad_i64_i32 v[14:15], s[24:25], v18, s22, v[46:47]
	global_load_dwordx4 v[14:17], v[14:15], off
	s_and_b64 vcc, exec, s[4:5]
	v_mov_b32_e32 v52, v44
	s_cbranch_vccnz .LBB0_39
	s_nop 0
	v_mul_f32_e32 v52, v44, v162
.LBB0_39:
	v_or_b32_e32 v26, 52, v51
	v_mad_i64_i32 v[18:19], s[24:25], v26, s22, v[46:47]
	global_load_dwordx4 v[18:21], v[18:19], off
	s_and_b64 vcc, exec, s[4:5]
	v_mov_b32_e32 v54, v44
	s_cbranch_vccnz .LBB0_41
	s_nop 0
	v_mul_f32_e32 v54, v44, v163
.LBB0_41:
	v_or_b32_e32 v30, 56, v51
	v_mad_i64_i32 v[26:27], s[24:25], v30, s22, v[46:47]
	global_load_dwordx4 v[26:29], v[26:27], off
	s_and_b64 vcc, exec, s[4:5]
	v_mov_b32_e32 v56, v44
	s_cbranch_vccnz .LBB0_43
	s_nop 0
	v_mul_f32_e32 v56, v44, v164
.LBB0_43:
	v_or_b32_e32 v35, 60, v51
	v_mad_i64_i32 v[30:31], s[24:25], v35, s22, v[46:47]
	global_load_dwordx4 v[30:33], v[30:31], off
	s_and_b64 vcc, exec, s[4:5]
	s_cbranch_vccnz .LBB0_12
	s_nop 0
	v_mul_f32_e32 v44, v44, v165
	s_branch .LBB0_12

.LBB0_963:
	s_ashr_i32 s10, s7, 31
	s_lshr_b32 s10, s10, 27
	s_add_i32 s10, s7, s10
	s_ashr_i32 s10, s10, 5
	s_lshl_b32 s26, s10, 6
	s_lshl_b32 s10, s10, 11
	s_sub_i32 s28, s1, s10
	v_or_b32_e32 v40, s26, v43
	s_ashr_i32 s29, s28, 31
	v_ashrrev_i32_e32 v41, 31, v40
	v_lshl_add_u64 v[38:39], s[28:29], 2, v[36:37]
	v_lshlrev_b64 v[4:5], 13, v[40:41]
	v_lshl_add_u64 v[4:5], v[38:39], 0, v[4:5]
	global_load_dwordx4 v[4:7], v[4:5], off
	v_cndmask_b32_e64 v8, 0, 1, s[4:5]
	v_cmp_ne_u32_e64 s[38:39], 1, v8
	s_andn2_b64 vcc, exec, s[4:5]
	v_mov_b32_e32 v42, v51
	s_cbranch_vccnz .LBB0_965
	v_and_b32_e32 v8, 0xc3, v40
	v_lshlrev_b32_e32 v8, 2, v8
	global_load_dword v150, v8, s[12:13]
	global_load_dword v151, v8, s[12:13] offset:16
	global_load_dword v152, v8, s[12:13] offset:32
	global_load_dword v153, v8, s[12:13] offset:48
	global_load_dword v154, v8, s[12:13] offset:64
	global_load_dword v155, v8, s[12:13] offset:80
	global_load_dword v156, v8, s[12:13] offset:96
	global_load_dword v157, v8, s[12:13] offset:112
	global_load_dword v158, v8, s[12:13] offset:128
	global_load_dword v159, v8, s[12:13] offset:144
	global_load_dword v160, v8, s[12:13] offset:160
	global_load_dword v161, v8, s[12:13] offset:176
	global_load_dword v162, v8, s[12:13] offset:192
	global_load_dword v163, v8, s[12:13] offset:208
	global_load_dword v164, v8, s[12:13] offset:224
	global_load_dword v165, v8, s[12:13] offset:240
	s_waitcnt vmcnt(0)
	v_mul_f32_e32 v42, v51, v150
.LBB0_965:
	v_or_b32_e32 v12, 4, v40
	v_ashrrev_i32_e32 v13, 31, v12
	v_lshlrev_b64 v[8:9], 13, v[12:13]
	v_lshl_add_u64 v[8:9], v[38:39], 0, v[8:9]
	global_load_dwordx4 v[8:11], v[8:9], off
	s_and_b64 vcc, exec, s[38:39]
	v_mov_b32_e32 v44, v51
	s_cbranch_vccnz .LBB0_967
	s_nop 0
	v_mul_f32_e32 v44, v51, v151
.LBB0_967:
	v_or_b32_e32 v16, 8, v40
	v_ashrrev_i32_e32 v17, 31, v16
	v_lshlrev_b64 v[12:13], 13, v[16:17]
	v_lshl_add_u64 v[12:13], v[38:39], 0, v[12:13]
	global_load_dwordx4 v[12:15], v[12:13], off
	s_and_b64 vcc, exec, s[38:39]
	v_mov_b32_e32 v46, v51
	s_cbranch_vccnz .LBB0_969
	s_nop 0
	v_mul_f32_e32 v46, v51, v152
.LBB0_969:
	v_or_b32_e32 v20, 12, v40
	v_ashrrev_i32_e32 v21, 31, v20
	v_lshlrev_b64 v[16:17], 13, v[20:21]
	v_lshl_add_u64 v[16:17], v[38:39], 0, v[16:17]
	global_load_dwordx4 v[16:19], v[16:17], off
	s_and_b64 vcc, exec, s[38:39]
	v_mov_b32_e32 v48, v51
	s_cbranch_vccnz .LBB0_971
	s_nop 0
	v_mul_f32_e32 v48, v51, v153
.LBB0_971:
	v_or_b32_e32 v24, 16, v40
	v_ashrrev_i32_e32 v25, 31, v24
	v_lshlrev_b64 v[20:21], 13, v[24:25]
	v_lshl_add_u64 v[20:21], v[38:39], 0, v[20:21]
	global_load_dwordx4 v[20:23], v[20:21], off
	s_and_b64 vcc, exec, s[38:39]
	v_mov_b32_e32 v50, v51
	s_cbranch_vccnz .LBB0_973
	s_nop 0
	v_mul_f32_e32 v50, v51, v154
.LBB0_973:
	v_or_b32_e32 v28, 20, v40
	v_ashrrev_i32_e32 v29, 31, v28
	v_lshlrev_b64 v[24:25], 13, v[28:29]
	v_lshl_add_u64 v[24:25], v[38:39], 0, v[24:25]
	global_load_dwordx4 v[24:27], v[24:25], off
	s_and_b64 vcc, exec, s[38:39]
	v_mov_b32_e32 v52, v51
	s_cbranch_vccnz .LBB0_975
	s_nop 0
	v_mul_f32_e32 v52, v51, v155
.LBB0_975:
	v_or_b32_e32 v32, 24, v40
	v_ashrrev_i32_e32 v33, 31, v32
	v_lshlrev_b64 v[28:29], 13, v[32:33]
	v_lshl_add_u64 v[28:29], v[38:39], 0, v[28:29]
	global_load_dwordx4 v[28:31], v[28:29], off
	s_and_b64 vcc, exec, s[38:39]
	v_mov_b32_e32 v54, v51
	s_cbranch_vccnz .LBB0_977
	s_nop 0
	v_mul_f32_e32 v54, v51, v156
.LBB0_977:
	v_or_b32_e32 v58, 28, v40
	v_ashrrev_i32_e32 v59, 31, v58
	v_lshlrev_b64 v[32:33], 13, v[58:59]
	v_lshl_add_u64 v[32:33], v[38:39], 0, v[32:33]
	global_load_dwordx4 v[32:35], v[32:33], off
	s_and_b64 vcc, exec, s[38:39]
	v_mov_b32_e32 v56, v51
	s_cbranch_vccnz .LBB0_979
	s_nop 0
	v_mul_f32_e32 v56, v51, v157
.LBB0_979:
	s_waitcnt vmcnt(7)
	v_pk_mul_f32 v[6:7], v[6:7], v[42:43] op_sel_hi:[1,0]
	v_pk_mul_f32 v[4:5], v[4:5], v[42:43] op_sel_hi:[1,0]
	v_add_u32_e32 v53, v47, v45
	ds_write_b128 v53, v[4:7]
	s_waitcnt vmcnt(6)
	v_pk_mul_f32 v[6:7], v[10:11], v[44:45] op_sel_hi:[1,0]
	v_pk_mul_f32 v[4:5], v[8:9], v[44:45] op_sel_hi:[1,0]
	ds_write_b128 v53, v[4:7] offset:1088
	s_waitcnt vmcnt(5)
	v_pk_mul_f32 v[6:7], v[14:15], v[46:47] op_sel_hi:[1,0]
	v_pk_mul_f32 v[4:5], v[12:13], v[46:47] op_sel_hi:[1,0]
	ds_write_b128 v53, v[4:7] offset:2176
	s_waitcnt vmcnt(4)
	v_pk_mul_f32 v[6:7], v[18:19], v[48:49] op_sel_hi:[1,0]
	v_pk_mul_f32 v[4:5], v[16:17], v[48:49] op_sel_hi:[1,0]
	ds_write_b128 v53, v[4:7] offset:3264
	s_waitcnt vmcnt(3)
	v_pk_mul_f32 v[6:7], v[22:23], v[50:51] op_sel_hi:[1,0]
	v_pk_mul_f32 v[4:5], v[20:21], v[50:51] op_sel_hi:[1,0]
	ds_write_b128 v53, v[4:7] offset:4352
	s_waitcnt vmcnt(2)
	v_pk_mul_f32 v[6:7], v[26:27], v[52:53] op_sel_hi:[1,0]
	v_pk_mul_f32 v[4:5], v[24:25], v[52:53] op_sel_hi:[1,0]
	ds_write_b128 v53, v[4:7] offset:5440
	s_waitcnt vmcnt(1)
	v_pk_mul_f32 v[6:7], v[30:31], v[54:55] op_sel_hi:[1,0]
	v_pk_mul_f32 v[4:5], v[28:29], v[54:55] op_sel_hi:[1,0]
	v_or_b32_e32 v8, 32, v40
	ds_write_b128 v53, v[4:7] offset:6528
	s_waitcnt vmcnt(0)
	v_pk_mul_f32 v[6:7], v[34:35], v[56:57] op_sel_hi:[1,0]
	v_pk_mul_f32 v[4:5], v[32:33], v[56:57] op_sel_hi:[1,0]
	v_ashrrev_i32_e32 v9, 31, v8
	ds_write_b128 v53, v[4:7] offset:7616
	v_lshlrev_b64 v[4:5], 13, v[8:9]
	v_lshl_add_u64 v[4:5], v[38:39], 0, v[4:5]
	global_load_dwordx4 v[4:7], v[4:5], off
	s_and_b64 vcc, exec, s[38:39]
	v_mov_b32_e32 v42, v51
	s_cbranch_vccnz .LBB0_981
	s_nop 0
	v_mul_f32_e32 v42, v51, v158
.LBB0_981:
	v_or_b32_e32 v12, 36, v40
	v_ashrrev_i32_e32 v13, 31, v12
	v_lshlrev_b64 v[8:9], 13, v[12:13]
	v_lshl_add_u64 v[8:9], v[38:39], 0, v[8:9]
	global_load_dwordx4 v[8:11], v[8:9], off
	s_and_b64 vcc, exec, s[38:39]
	v_mov_b32_e32 v44, v51
	s_cbranch_vccnz .LBB0_983
	s_nop 0
	v_mul_f32_e32 v44, v51, v159
.LBB0_983:
	v_or_b32_e32 v16, 40, v40
	v_ashrrev_i32_e32 v17, 31, v16
	v_lshlrev_b64 v[12:13], 13, v[16:17]
	v_lshl_add_u64 v[12:13], v[38:39], 0, v[12:13]
	global_load_dwordx4 v[12:15], v[12:13], off
	s_and_b64 vcc, exec, s[38:39]
	v_mov_b32_e32 v46, v51
	s_cbranch_vccnz .LBB0_985
	s_nop 0
	v_mul_f32_e32 v46, v51, v160
.LBB0_985:
	v_or_b32_e32 v20, 44, v40
	v_ashrrev_i32_e32 v21, 31, v20
	v_lshlrev_b64 v[16:17], 13, v[20:21]
	v_lshl_add_u64 v[16:17], v[38:39], 0, v[16:17]
	global_load_dwordx4 v[16:19], v[16:17], off
	s_and_b64 vcc, exec, s[38:39]
	v_mov_b32_e32 v48, v51
	s_cbranch_vccnz .LBB0_987
	s_nop 0
	v_mul_f32_e32 v48, v51, v161
.LBB0_987:
	v_or_b32_e32 v24, 48, v40
	v_ashrrev_i32_e32 v25, 31, v24
	v_lshlrev_b64 v[20:21], 13, v[24:25]
	v_lshl_add_u64 v[20:21], v[38:39], 0, v[20:21]
	global_load_dwordx4 v[20:23], v[20:21], off
	s_and_b64 vcc, exec, s[38:39]
	v_mov_b32_e32 v50, v51
	s_cbranch_vccnz .LBB0_989
	s_nop 0
	v_mul_f32_e32 v50, v51, v162
.LBB0_989:
	v_or_b32_e32 v28, 52, v40
	v_ashrrev_i32_e32 v29, 31, v28
	v_lshlrev_b64 v[24:25], 13, v[28:29]
	v_lshl_add_u64 v[24:25], v[38:39], 0, v[24:25]
	global_load_dwordx4 v[24:27], v[24:25], off
	s_and_b64 vcc, exec, s[38:39]
	v_mov_b32_e32 v52, v51
	s_cbranch_vccnz .LBB0_991
	s_nop 0
	v_mul_f32_e32 v52, v51, v163
.LBB0_991:
	v_or_b32_e32 v32, 56, v40
	v_ashrrev_i32_e32 v33, 31, v32
	v_lshlrev_b64 v[28:29], 13, v[32:33]
	v_lshl_add_u64 v[28:29], v[38:39], 0, v[28:29]
	global_load_dwordx4 v[28:31], v[28:29], off
	s_and_b64 vcc, exec, s[38:39]
	v_mov_b32_e32 v54, v51
	s_cbranch_vccnz .LBB0_993
	s_nop 0
	v_mul_f32_e32 v54, v51, v164
.LBB0_993:
	v_or_b32_e32 v40, 60, v40
	v_ashrrev_i32_e32 v41, 31, v40
	v_lshlrev_b64 v[32:33], 13, v[40:41]
	v_lshl_add_u64 v[32:33], v[38:39], 0, v[32:33]
	global_load_dwordx4 v[32:35], v[32:33], off
	s_and_b64 vcc, exec, s[38:39]
	v_mov_b32_e32 v38, v51
	s_cbranch_vccnz .LBB0_962
	s_nop 0
	v_mul_f32_e32 v38, v51, v165
	s_branch .LBB0_962
